# speedup vs baseline: 1.0163x; 1.0019x over previous
; template <int MODE>
; __device__ __forceinline__ void attn_item(const Params& P, int b, int h, int qb, char* lds) {
;     ...
;       for (int r = 0; r < 16; ++r) { p0[r] = __builtin_amdgcn_exp2f(p0[r]); p1[r] = __builtin_amdgcn_exp2f(p1[r]); }
;       if (MODE == 0) {
;         const int w0 = (int)((unsigned)(mcur) >> (4 * hi)), w1 = (int)((unsigned)(mcur >> 32) >> (4 * hi));
; #pragma unroll
;         for (int r = 0; r < 16; ++r) {
;           const int c = (r & 3) + 8 * (r >> 2);
;           p0[r] = __uint_as_float(__float_as_uint(p0[r]) & (unsigned)__builtin_amdgcn_sbfe(w0, c, 1));
;           p1[r] = __uint_as_float(__float_as_uint(p1[r]) & (unsigned)__builtin_amdgcn_sbfe(w1, c, 1));
;         }
;       }
;       bf16x8 pa0, pa1, pa2, pa3;
;     ...
;       PK4(p0, 0, pa0); PK4(p0, 8, pa1); PK4(p1, 0, pa2); PK4(p1, 8, pa3);
;     ...
;       if (__any(alpha < 1.f)) {
;         if (hi == 0) al_l[r32] = alpha;
;         __builtin_amdgcn_wave_barrier();
; #pragma unroll
;         for (int q = 0; q < 4; ++q) {
;           const f32x4 a4 = *(const f32x4*)(al_l + 8 * q + 4 * hi);
; #pragma unroll
;           for (int d = 0; d < 4; ++d) { o[d][q * 4 + 0] *= a4[0]; o[d][q * 4 + 1] *= a4[1]; o[d][q * 4 + 2] *= a4[2]; o[d][q * 4 + 3] *= a4[3]; }
;           ol[q * 4 + 0] *= a4[0]; ol[q * 4 + 1] *= a4[1]; ol[q * 4 + 2] *= a4[2]; ol[q * 4 + 3] *= a4[3];
;         }
;         __builtin_amdgcn_wave_barrier();
;       }
.LBB0_693:
	v_lshrrev_b32_e32 v244, v170, v166
	v_lshrrev_b32_e32 v245, v170, v167
	v_exp_f32_e32 v112, v112
	v_bfe_i32 v246, v244, 0, 1
	v_exp_f32_e32 v113, v113
	v_bfe_i32 v247, v244, 1, 1
	v_and_b32_e32 v112, v112, v246
	v_exp_f32_e32 v114, v114
	v_bfe_i32 v246, v244, 2, 1
	v_and_b32_e32 v113, v113, v247
	v_exp_f32_e32 v115, v115
	v_bfe_i32 v247, v244, 3, 1
	v_and_b32_e32 v114, v114, v246
	v_exp_f32_e32 v116, v116
	v_bfe_i32 v246, v244, 8, 1
	v_and_b32_e32 v115, v115, v247
	v_exp_f32_e32 v117, v117
	v_bfe_i32 v247, v244, 9, 1
	v_and_b32_e32 v116, v116, v246
	v_exp_f32_e32 v118, v118
	v_bfe_i32 v246, v244, 10, 1
	v_and_b32_e32 v117, v117, v247
	v_exp_f32_e32 v119, v119
	v_bfe_i32 v247, v244, 11, 1
	v_and_b32_e32 v118, v118, v246
	v_exp_f32_e32 v120, v120
	v_bfe_i32 v246, v244, 16, 1
	v_and_b32_e32 v119, v119, v247
	v_exp_f32_e32 v121, v121
	v_bfe_i32 v247, v244, 17, 1
	v_and_b32_e32 v120, v120, v246
	v_exp_f32_e32 v122, v122
	v_bfe_i32 v246, v244, 18, 1
	v_and_b32_e32 v121, v121, v247
	v_exp_f32_e32 v123, v123
	v_bfe_i32 v247, v244, 19, 1
	v_and_b32_e32 v122, v122, v246
	v_exp_f32_e32 v124, v124
	v_bfe_i32 v246, v244, 24, 1
	v_and_b32_e32 v123, v123, v247
	v_exp_f32_e32 v125, v125
	v_bfe_i32 v247, v244, 25, 1
	v_and_b32_e32 v124, v124, v246
	v_exp_f32_e32 v126, v126
	v_bfe_i32 v246, v244, 26, 1
	v_and_b32_e32 v125, v125, v247
	v_exp_f32_e32 v127, v127
	v_bfe_i32 v247, v244, 27, 1
	v_and_b32_e32 v126, v126, v246
	v_exp_f32_e32 v96, v96
	v_bfe_i32 v246, v245, 0, 1
	v_and_b32_e32 v127, v127, v247
	v_exp_f32_e32 v97, v97
	v_bfe_i32 v247, v245, 1, 1
	v_and_b32_e32 v96, v96, v246
	v_exp_f32_e32 v98, v98
	v_bfe_i32 v246, v245, 2, 1
	v_and_b32_e32 v97, v97, v247
	v_exp_f32_e32 v99, v99
	v_bfe_i32 v247, v245, 3, 1
	v_and_b32_e32 v98, v98, v246
	v_exp_f32_e32 v100, v100
	v_bfe_i32 v246, v245, 8, 1
	v_and_b32_e32 v99, v99, v247
	v_exp_f32_e32 v101, v101
	v_bfe_i32 v247, v245, 9, 1
	v_and_b32_e32 v100, v100, v246
	v_exp_f32_e32 v102, v102
	v_bfe_i32 v246, v245, 10, 1
	v_and_b32_e32 v101, v101, v247
	v_exp_f32_e32 v103, v103
	v_bfe_i32 v247, v245, 11, 1
	v_and_b32_e32 v102, v102, v246
	v_exp_f32_e32 v104, v104
	v_bfe_i32 v246, v245, 16, 1
	v_and_b32_e32 v103, v103, v247
	v_exp_f32_e32 v105, v105
	v_bfe_i32 v247, v245, 17, 1
	v_and_b32_e32 v104, v104, v246
	v_exp_f32_e32 v106, v106
	v_bfe_i32 v246, v245, 18, 1
	v_and_b32_e32 v105, v105, v247
	v_exp_f32_e32 v107, v107
	v_bfe_i32 v247, v245, 19, 1
	v_and_b32_e32 v106, v106, v246
	v_exp_f32_e32 v108, v108
	v_bfe_i32 v246, v245, 24, 1
	v_and_b32_e32 v107, v107, v247
	v_exp_f32_e32 v109, v109
	v_bfe_i32 v247, v245, 25, 1
	v_and_b32_e32 v108, v108, v246
	v_exp_f32_e32 v110, v110
	v_bfe_i32 v246, v245, 26, 1
	v_and_b32_e32 v109, v109, v247
	v_exp_f32_e32 v111, v111
	v_bfe_i32 v247, v245, 27, 1
	v_and_b32_e32 v110, v110, v246
	s_nop 0
	v_and_b32_e32 v111, v111, v247
	v_cvt_pk_bf16_f32 v2, v112, v113
	v_cvt_pk_bf16_f32 v3, v114, v115
	v_cvt_pk_bf16_f32 v4, v116, v117
	v_cvt_pk_bf16_f32 v5, v118, v119
	v_cvt_pk_bf16_f32 v6, v120, v121
	v_cvt_pk_bf16_f32 v7, v122, v123
	v_cvt_pk_bf16_f32 v8, v124, v125
	v_cvt_pk_bf16_f32 v9, v126, v127
	v_permlane32_swap_b32_e32 v2, v4
	v_permlane32_swap_b32_e32 v3, v5
	v_cvt_pk_bf16_f32 v10, v96, v97
	v_cvt_pk_bf16_f32 v11, v98, v99
	v_cvt_pk_bf16_f32 v12, v100, v101
	v_cvt_pk_bf16_f32 v13, v102, v103
	v_permlane32_swap_b32_e32 v6, v8
	v_permlane32_swap_b32_e32 v7, v9
	v_cvt_pk_bf16_f32 v96, v104, v105
	v_cvt_pk_bf16_f32 v97, v106, v107
	v_cvt_pk_bf16_f32 v98, v108, v109
	v_cvt_pk_bf16_f32 v99, v110, v111
	v_permlane32_swap_b32_e32 v10, v12
	v_permlane32_swap_b32_e32 v11, v13
	s_nop 1
	v_permlane32_swap_b32_e32 v96, v98
	v_permlane32_swap_b32_e32 v97, v99
	v_cmp_gt_f32_e32 vcc, 1.0, v0
	s_cbranch_vccz .LBB0_697
	s_and_saveexec_b64 s[0:1], s[6:7]
	ds_write_b32 v173, v0
	s_or_b64 exec, exec, s[0:1]
	ds_read_b128 v[100:103], v172 offset:96
	ds_read_b128 v[104:107], v172 offset:64
	ds_read_b128 v[108:111], v172 offset:32
	ds_read_b128 v[112:115], v172
	s_waitcnt lgkmcnt(0)
	v_pk_mul_f32 v[78:79], v[78:79], v[102:103]
	v_pk_mul_f32 v[74:75], v[74:75], v[106:107]
	v_pk_mul_f32 v[70:71], v[70:71], v[110:111]
	v_pk_mul_f32 v[66:67], v[66:67], v[114:115]
	v_pk_mul_f32 v[76:77], v[76:77], v[100:101]
	v_pk_mul_f32 v[72:73], v[72:73], v[104:105]
	v_pk_mul_f32 v[68:69], v[68:69], v[108:109]
	v_pk_mul_f32 v[64:65], v[64:65], v[112:113]
	v_pk_mul_f32 v[62:63], v[62:63], v[102:103]
	v_pk_mul_f32 v[58:59], v[58:59], v[106:107]
	v_pk_mul_f32 v[54:55], v[54:55], v[110:111]
	v_pk_mul_f32 v[50:51], v[50:51], v[114:115]
	v_pk_mul_f32 v[60:61], v[60:61], v[100:101]
	v_pk_mul_f32 v[56:57], v[56:57], v[104:105]
	v_pk_mul_f32 v[52:53], v[52:53], v[108:109]
	v_pk_mul_f32 v[48:49], v[48:49], v[112:113]
	v_pk_mul_f32 v[46:47], v[46:47], v[102:103]
	v_pk_mul_f32 v[42:43], v[42:43], v[106:107]
	v_pk_mul_f32 v[38:39], v[38:39], v[110:111]
	v_pk_mul_f32 v[34:35], v[34:35], v[114:115]
	v_pk_mul_f32 v[44:45], v[44:45], v[100:101]
	v_pk_mul_f32 v[40:41], v[40:41], v[104:105]
	v_pk_mul_f32 v[36:37], v[36:37], v[108:109]
	v_pk_mul_f32 v[32:33], v[32:33], v[112:113]
	v_pk_mul_f32 v[30:31], v[30:31], v[102:103]
	v_pk_mul_f32 v[26:27], v[26:27], v[106:107]
	v_pk_mul_f32 v[22:23], v[22:23], v[110:111]
	v_pk_mul_f32 v[18:19], v[18:19], v[114:115]
	v_pk_mul_f32 v[28:29], v[28:29], v[100:101]
	v_pk_mul_f32 v[24:25], v[24:25], v[104:105]
	v_pk_mul_f32 v[20:21], v[20:21], v[108:109]
	v_pk_mul_f32 v[16:17], v[16:17], v[112:113]
	v_pk_mul_f32 v[94:95], v[94:95], v[102:103]
	v_pk_mul_f32 v[90:91], v[90:91], v[106:107]
	v_pk_mul_f32 v[86:87], v[86:87], v[110:111]
	v_pk_mul_f32 v[82:83], v[82:83], v[114:115]
	v_pk_mul_f32 v[92:93], v[92:93], v[100:101]
	v_pk_mul_f32 v[88:89], v[88:89], v[104:105]
	v_pk_mul_f32 v[84:85], v[84:85], v[108:109]
	v_pk_mul_f32 v[80:81], v[80:81], v[112:113]
